# S5 final pass: U-tile LDS staging deferred behind the direction-0 fragment loads
# baseline (speedup 1.0000x reference)
.LBB0_280:
	s_and_b32 s4, s17, 8
	v_mov_b64_e32 v[4:5], s[0:1]
	s_add_i32 s4, s4, s11
	v_mad_i64_i32 v[2:3], s[0:1], v2, s94, v[4:5]
	s_lshl_b32 s0, s4, 4
	s_ashr_i32 s1, s0, 31
	s_lshr_b32 s5, s6, 6
	v_lshl_add_u64 v[2:3], s[0:1], 1, v[2:3]
	s_mov_b64 s[6:7], 0xe001000
	v_lshl_add_u64 v[6:7], v[2:3], 0, s[6:7]
	v_add_co_u32_e32 v2, vcc, 0xe001000, v2
	s_mulk_i32 s5, 0x3e00
	s_nop 0
	v_addc_co_u32_e32 v3, vcc, 0, v3, vcc
	global_load_dwordx4 v[222:225], v[2:3], off
	s_nop 0
	global_load_dwordx4 v[226:229], v[6:7], off offset:16
	s_add_i32 s5, s5, 0
	v_mad_u32_u24 v0, v0, 48, s5
	v_mov_b32_e32 v62, v204
	s_add_i32 s6, s4, s21
	s_ashr_i32 s7, s6, 31
	s_lshl_b64 s[26:27], s[6:7], 13
	v_mov_b32_e32 v230, v0
	v_mov_b32_e32 v0, s59
	s_waitcnt lgkmcnt(0)
	ds_read_b64 v[2:3], v0
	v_and_b32_e32 v61, 63, v62
	v_readfirstlane_b32 s5, v62
	s_lshr_b32 s5, s5, 6
	s_mulk_i32 s5, 0x3e00
	s_waitcnt lgkmcnt(0)
	v_readfirstlane_b32 s8, v2
	v_lshl_or_b32 v2, s6, 6, v61
	v_readfirstlane_b32 s9, v3
	v_ashrrev_i32_e32 v3, 31, v2
	s_add_i32 s28, s5, 0
	v_lshl_add_u64 v[2:3], v[2:3], 4, s[8:9]
	s_mov_b32 s5, 0x200000
	v_add_co_u32_e32 v2, vcc, s5, v2
	s_add_u32 s26, s8, s26
	v_and_b32_e32 v60, 15, v62
	v_addc_co_u32_e32 v3, vcc, 0, v3, vcc
	s_addc_u32 s27, s9, s27
	v_and_b32_e32 v0, 48, v62
	global_load_dwordx2 v[6:7], v[2:3], off
	v_lshl_add_u64 v[2:3], s[26:27], 0, v[0:1]
	v_lshlrev_b32_e32 v4, 6, v60
	v_mov_b32_e32 v5, v1
	v_lshl_add_u64 v[2:3], v[2:3], 0, v[4:5]
	s_mov_b32 s5, 0x240000
	s_waitcnt lgkmcnt(0)
	v_add_co_u32_e32 v8, vcc, s5, v2
	s_mov_b64 s[26:27], 0x240000
	s_nop 0
	v_addc_co_u32_e32 v9, vcc, 0, v3, vcc
	s_mov_b32 s5, 0x241000
	v_lshl_add_u64 v[4:5], v[2:3], 0, s[26:27]
	v_add_co_u32_e32 v2, vcc, s5, v2
	s_lshl_b64 s[6:7], s[6:7], 12
	s_nop 0
	v_addc_co_u32_e32 v3, vcc, 0, v3, vcc
	s_add_u32 s6, s8, s6
	global_load_dwordx4 v[52:55], v[8:9], off
	global_load_dwordx4 v[56:59], v[4:5], off offset:1024
	global_load_dwordx4 v[44:47], v[4:5], off offset:2048
	global_load_dwordx4 v[48:51], v[4:5], off offset:3072
	global_load_dwordx4 v[40:43], v[2:3], off
	global_load_dwordx4 v[36:39], v[2:3], off offset:1024
	global_load_dwordx4 v[32:35], v[2:3], off offset:2048
	global_load_dwordx4 v[28:31], v[2:3], off offset:3072
	s_addc_u32 s7, s9, s7
	v_lshlrev_b32_e32 v2, 8, v60
	v_mov_b32_e32 v3, v1
	v_lshl_add_u64 v[2:3], s[6:7], 0, v[2:3]
	v_lshl_add_u64 v[2:3], v[2:3], 0, v[0:1]
	s_mov_b64 s[6:7], 0x380000
	v_lshl_add_u64 v[4:5], v[2:3], 0, s[6:7]
	s_mov_b32 s5, 0x380000
	s_lshl_b32 s26, s20, 1
	s_mul_i32 s6, s20, 0x88
	s_ashr_i32 s27, s22, 31
	v_add_co_u32_e32 v2, vcc, s5, v2
	s_mul_hi_i32 s5, s26, 0x44
	s_add_u32 s6, s6, s22
	s_addc_u32 s7, s5, s27
	s_ashr_i32 s5, s4, 31
	s_lshl_b64 s[38:39], s[6:7], 10
	s_lshl_b64 s[6:7], s[4:5], 6
	s_add_u32 s5, s38, s6
	v_addc_co_u32_e32 v3, vcc, 0, v3, vcc
	s_addc_u32 s29, s39, s7
	global_load_dwordx4 v[24:27], v[2:3], off
	global_load_dwordx4 v[20:23], v[4:5], off offset:64
	global_load_dwordx4 v[16:19], v[4:5], off offset:128
	global_load_dwordx4 v[12:15], v[4:5], off offset:192
	v_or_b32_e32 v2, s5, v61
	v_mov_b32_e32 v3, s29
	v_lshl_add_u64 v[2:3], v[2:3], 3, s[8:9]
	v_add_co_u32_e32 v2, vcc, 0x1500000, v2
	v_mov_b32_e32 v8, 0
	s_nop 0
	v_addc_co_u32_e32 v3, vcc, 0, v3, vcc
	global_load_dwordx2 v[10:11], v[2:3], off
	v_add_u32_e32 v2, s28, v0
	v_cmp_gt_u32_e32 vcc, 32, v61
	v_mad_u32_u24 v95, v60, 48, v2
	v_mov_b32_e32 v2, 0
	v_mov_b32_e32 v3, 0
	v_mov_b32_e32 v4, 0
	v_mov_b32_e32 v5, 0
	s_waitcnt vmcnt(14)
	ds_write_b128 v230, v[222:225]
	ds_write_b128 v230, v[226:229] offset:16
	s_and_saveexec_b64 s[8:9], vcc
	ds_read_b128 v[2:5], v95
	s_or_b64 exec, exec, s[8:9]
	s_waitcnt vmcnt(0) lgkmcnt(0)
	v_mfma_f32_16x16x32_bf16 v[64:67], v[2:5], v[52:55], 0
	v_bfe_u32 v9, v62, 4, 2
	v_lshlrev_b32_e32 v79, 2, v61
	v_mov_b32_e32 v61, s28
	v_mfma_f32_16x16x32_bf16 v[70:73], v[2:5], v[56:59], 0
	s_movk_i32 s5, 0x110
	v_lshlrev_b32_e32 v68, 2, v60
	v_mad_u32_u24 v112, v60, s5, v61
	v_mul_u32_u24_e32 v9, 0x840, v9
	v_mfma_f32_16x16x32_bf16 v[60:63], v[2:5], v[44:47], 0
	v_add3_u32 v9, s28, v68, v9
	v_add_u32_e32 v68, 0xc00, v9
	v_add_u32_e32 v69, 0x1000, v9
	v_mfma_f32_16x16x32_bf16 v[74:77], v[2:5], v[48:51], 0
	ds_write2_b32 v68, v64, v70 offset1:16
	ds_write2_b32 v68, v65, v71 offset0:132 offset1:148
	ds_write2_b32 v69, v66, v72 offset0:8 offset1:24
	v_mfma_f32_16x16x32_bf16 v[80:83], v[2:5], v[40:43], 0
	ds_write2_b32 v69, v67, v73 offset0:140 offset1:156
	s_nop 2
	ds_write2_b32 v68, v60, v74 offset0:32 offset1:48
	ds_write2_b32 v68, v61, v75 offset0:164 offset1:180
	v_add_u32_e32 v70, s28, v79
	v_mul_f32_e32 v9, v7, v11
	v_mfma_f32_16x16x32_bf16 v[64:67], v[2:5], v[36:39], 0
	ds_write2_b32 v69, v62, v76 offset0:40 offset1:56
	ds_write2_b32 v69, v63, v77 offset0:172 offset1:188
	s_nop 5
	ds_write2_b32 v68, v80, v64 offset0:64 offset1:80
	ds_write2_b32 v68, v81, v65 offset0:196 offset1:212
	ds_write2_b32 v69, v82, v66 offset0:72 offset1:88
	ds_write2_b32 v69, v83, v67 offset0:204 offset1:220
	v_mfma_f32_16x16x32_bf16 v[60:63], v[2:5], v[32:35], 0
	v_add_u32_e32 v71, 16, v70
	v_fma_f32 v9, v6, v10, -v9
	v_add_u32_e32 v72, 32, v70
	v_mfma_f32_16x16x32_bf16 v[2:5], v[2:5], v[28:31], 0
	s_nop 7
	ds_write2_b32 v68, v60, v2 offset0:96 offset1:112
	ds_write2_b32 v68, v61, v3 offset0:228 offset1:244
	ds_write2_b32 v69, v62, v4 offset0:104 offset1:120
	ds_write2_b32 v69, v63, v5 offset0:236 offset1:252
	s_waitcnt lgkmcnt(0)
	ds_read2st64_b32 v[2:3], v70 offset0:12 offset1:13
	ds_read2st64_b32 v[4:5], v71 offset0:14 offset1:15
	ds_read2st64_b32 v[60:61], v72 offset0:16 offset1:17
	v_add_u32_e32 v87, 0x2c00, v70
	v_add_u32_e32 v73, 48, v70
	s_waitcnt lgkmcnt(2)
	v_add_f32_e32 v2, v9, v2
	v_mul_f32_e32 v9, v7, v10
	v_fmac_f32_e32 v9, v6, v11
	v_add_f32_e32 v3, v9, v3
	v_cvt_pk_bf16_f32 v9, v2, v3
	s_waitcnt lgkmcnt(1)
	v_fma_f32 v10, v7, v2, v5
	v_fma_f32 v4, v6, v2, v4
	v_fma_f32 v4, -v7, v3, v4
	v_fma_f32 v2, v6, v3, v10
	v_cvt_pk_bf16_f32 v3, v4, v2
	ds_write2_b32 v87, v9, v3 offset0:64 offset1:132
	ds_read2st64_b32 v[62:63], v73 offset0:18 offset1:19
	s_waitcnt lgkmcnt(2)
	v_fma_f32 v3, -v2, v7, v60
	v_fma_f32 v2, v2, v6, v61
	v_fma_f32 v2, v4, v7, v2
	v_fma_f32 v3, v4, v6, v3
	v_add_u32_e32 v74, 64, v70
	v_cvt_pk_bf16_f32 v4, v3, v2
	ds_read2st64_b32 v[64:65], v74 offset0:20 offset1:21
	s_waitcnt lgkmcnt(1)
	v_fma_f32 v5, -v2, v7, v62
	v_fma_f32 v2, v2, v6, v63
	v_fma_f32 v2, v3, v7, v2
	v_fma_f32 v5, v3, v6, v5
	v_cvt_pk_bf16_f32 v3, v5, v2
	v_add_u32_e32 v88, 0x2e00, v70
	v_add_u32_e32 v75, 0x50, v70
	ds_write2_b32 v88, v4, v3 offset0:72 offset1:140
	ds_read2st64_b32 v[66:67], v75 offset0:22 offset1:23
	s_waitcnt lgkmcnt(2)
	v_fma_f32 v4, v7, v5, v65
	v_fma_f32 v3, v6, v5, v64
	v_fma_f32 v3, -v7, v2, v3
	v_fma_f32 v2, v6, v2, v4
	v_add_u32_e32 v76, 0x60, v70
	v_cvt_pk_bf16_f32 v4, v3, v2
	ds_read2st64_b32 v[90:91], v76 offset0:24 offset1:25
	s_waitcnt lgkmcnt(1)
	v_fma_f32 v5, -v2, v7, v66
	v_fma_f32 v2, v2, v6, v67
	v_fma_f32 v2, v3, v7, v2
	v_fma_f32 v5, v3, v6, v5
	v_cvt_pk_bf16_f32 v3, v5, v2
	v_add_u32_e32 v89, 0x3000, v70
	v_add_u32_e32 v77, 0x70, v70
	ds_write2_b32 v89, v4, v3 offset0:80 offset1:148
	ds_read2st64_b32 v[92:93], v77 offset0:26 offset1:27
	s_waitcnt lgkmcnt(2)
	v_fma_f32 v4, v7, v5, v91
	v_fma_f32 v3, v6, v5, v90
	v_fma_f32 v3, -v7, v2, v3
	v_fma_f32 v2, v6, v2, v4
	v_add_u32_e32 v79, 0x80, v70
	v_cvt_pk_bf16_f32 v4, v3, v2
	ds_read2st64_b32 v[96:97], v79 offset0:28 offset1:29
	s_waitcnt lgkmcnt(1)
	v_fma_f32 v5, -v2, v7, v92
	v_fma_f32 v2, v2, v6, v93
	v_fma_f32 v2, v3, v7, v2
	v_fma_f32 v5, v3, v6, v5
	v_cvt_pk_bf16_f32 v3, v5, v2
	v_add_u32_e32 v90, 0x3200, v70
	v_add_u32_e32 v80, 0x90, v70
	ds_write2_b32 v90, v4, v3 offset0:88 offset1:156
	ds_read2st64_b32 v[98:99], v80 offset0:30 offset1:31
	s_waitcnt lgkmcnt(2)
	v_fma_f32 v4, v7, v5, v97
	v_fma_f32 v3, v6, v5, v96
	v_fma_f32 v3, -v7, v2, v3
	v_fma_f32 v2, v6, v2, v4
	v_add_u32_e32 v81, 0xa0, v70
	v_cvt_pk_bf16_f32 v4, v3, v2
	ds_read2st64_b32 v[100:101], v81 offset0:32 offset1:33
	s_waitcnt lgkmcnt(1)
	v_fma_f32 v5, -v2, v7, v98
	v_fma_f32 v2, v2, v6, v99
	v_fma_f32 v2, v3, v7, v2
	v_fma_f32 v5, v3, v6, v5
	v_cvt_pk_bf16_f32 v3, v5, v2
	v_add_u32_e32 v91, 0x3400, v70
	v_add_u32_e32 v82, 0xb0, v70
	ds_write2_b32 v91, v4, v3 offset0:96 offset1:164
	ds_read2st64_b32 v[102:103], v82 offset0:34 offset1:35
	s_waitcnt lgkmcnt(2)
	v_fma_f32 v4, v7, v5, v101
	v_fma_f32 v3, v6, v5, v100
	v_fma_f32 v3, -v7, v2, v3
	v_fma_f32 v2, v6, v2, v4
	v_add_u32_e32 v83, 0xc0, v70
	v_cvt_pk_bf16_f32 v4, v3, v2
	ds_read2st64_b32 v[104:105], v83 offset0:36 offset1:37
	s_waitcnt lgkmcnt(1)
	v_fma_f32 v5, -v2, v7, v102
	v_fma_f32 v2, v2, v6, v103
	v_fma_f32 v2, v3, v7, v2
	v_fma_f32 v5, v3, v6, v5
	v_cvt_pk_bf16_f32 v3, v5, v2
	v_add_u32_e32 v92, 0x3600, v70
	v_add_u32_e32 v84, 0xd0, v70
	ds_write2_b32 v92, v4, v3 offset0:104 offset1:172
	ds_read2st64_b32 v[106:107], v84 offset0:38 offset1:39
	s_waitcnt lgkmcnt(2)
	v_fma_f32 v4, v7, v5, v105
	v_fma_f32 v3, v6, v5, v104
	v_fma_f32 v3, -v7, v2, v3
	v_fma_f32 v2, v6, v2, v4
	v_add_u32_e32 v85, 0xe0, v70
	v_cvt_pk_bf16_f32 v4, v3, v2
	ds_read2st64_b32 v[108:109], v85 offset0:40 offset1:41
	s_waitcnt lgkmcnt(1)
	v_fma_f32 v5, -v2, v7, v106
	v_fma_f32 v2, v2, v6, v107
	v_fma_f32 v2, v3, v7, v2
	v_fma_f32 v5, v3, v6, v5
	v_cvt_pk_bf16_f32 v3, v5, v2
	v_add_u32_e32 v93, 0x3800, v70
	v_add_u32_e32 v86, 0xf0, v70
	ds_write2_b32 v93, v4, v3 offset0:112 offset1:180
	ds_read2st64_b32 v[110:111], v86 offset0:42 offset1:43
	s_waitcnt lgkmcnt(2)
	v_fma_f32 v4, v7, v5, v109
	v_fma_f32 v3, v6, v5, v108
	v_fma_f32 v3, -v7, v2, v3
	v_fma_f32 v2, v6, v2, v4
	v_cvt_pk_bf16_f32 v4, v3, v2
	s_waitcnt lgkmcnt(0)
	v_fma_f32 v5, v7, v3, v111
	v_fma_f32 v60, v6, v3, v110
	v_fma_f32 v60, -v7, v2, v60
	v_fma_f32 v61, v6, v2, v5
	v_cvt_pk_bf16_f32 v2, v60, v61
	v_add_u32_e32 v94, 0x3a00, v70
	ds_write2_b32 v94, v4, v2 offset0:120 offset1:188
	s_waitcnt lgkmcnt(0)
	v_add_u32_e32 v0, v112, v0
	ds_read_b128 v[2:5], v0 offset:11520
	ds_read_b128 v[62:65], v0 offset:11584
	s_waitcnt lgkmcnt(1)
	v_mfma_f32_16x16x32_bf16 v[2:5], v[2:5], v[24:27], 0
	ds_read_b128 v[96:99], v0 offset:11648
	v_mov_b32_e32 v9, 0
	v_mov_b32_e32 v10, 0
	s_waitcnt lgkmcnt(1)
	v_mfma_f32_16x16x32_bf16 v[2:5], v[62:65], v[20:23], v[2:5]
	ds_read_b128 v[62:65], v0 offset:11712
	v_mov_b32_e32 v11, 0
	s_waitcnt lgkmcnt(1)
	v_mfma_f32_16x16x32_bf16 v[2:5], v[96:99], v[16:19], v[2:5]
	s_waitcnt lgkmcnt(0)
	v_mfma_f32_16x16x32_bf16 v[2:5], v[62:65], v[12:15], v[2:5]
	s_and_saveexec_b64 s[8:9], vcc
	ds_read_b128 v[8:11], v95 offset:768
	s_or_b64 exec, exec, s[8:9]
	s_waitcnt lgkmcnt(0)
	v_mfma_f32_16x16x32_bf16 v[62:65], v[8:11], v[52:55], 0
	v_mul_f32_e32 v118, v7, v61
	v_fma_f32 v118, v6, v60, -v118
	v_mul_f32_e32 v60, v7, v60
	v_mfma_f32_16x16x32_bf16 v[96:99], v[8:11], v[56:59], 0
	s_nop 7
	ds_write2_b32 v68, v62, v96 offset1:16
	ds_write2_b32 v68, v63, v97 offset0:132 offset1:148
	ds_write2_b32 v69, v64, v98 offset0:8 offset1:24
	v_mfma_f32_16x16x32_bf16 v[100:103], v[8:11], v[44:47], 0
	v_fmac_f32_e32 v60, v6, v61
	v_mfma_f32_16x16x32_bf16 v[104:107], v[8:11], v[48:51], 0
	ds_write2_b32 v69, v65, v99 offset0:140 offset1:156
	s_nop 6
	ds_write2_b32 v68, v100, v104 offset0:32 offset1:48
	ds_write2_b32 v68, v101, v105 offset0:164 offset1:180
	v_mfma_f32_16x16x32_bf16 v[108:111], v[8:11], v[40:43], 0
	v_mfma_f32_16x16x32_bf16 v[62:65], v[8:11], v[36:39], 0
	ds_write2_b32 v69, v102, v106 offset0:40 offset1:56
	ds_write2_b32 v69, v103, v107 offset0:172 offset1:188
	s_nop 5
	ds_write2_b32 v68, v108, v62 offset0:64 offset1:80
	ds_write2_b32 v68, v109, v63 offset0:196 offset1:212
	ds_write2_b32 v69, v110, v64 offset0:72 offset1:88
	ds_write2_b32 v69, v111, v65 offset0:204 offset1:220
	v_mfma_f32_16x16x32_bf16 v[96:99], v[8:11], v[32:35], 0
	v_mfma_f32_16x16x32_bf16 v[8:11], v[8:11], v[28:31], 0
	s_nop 7
	ds_write2_b32 v68, v96, v8 offset0:96 offset1:112
	ds_write2_b32 v68, v97, v9 offset0:228 offset1:244
	ds_write2_b32 v69, v98, v10 offset0:104 offset1:120
	ds_write2_b32 v69, v99, v11 offset0:236 offset1:252
	s_waitcnt lgkmcnt(0)
	ds_read2st64_b32 v[8:9], v70 offset0:12 offset1:13
	ds_read2st64_b32 v[10:11], v71 offset0:14 offset1:15
	ds_read2st64_b32 v[62:63], v72 offset0:16 offset1:17
	ds_read2st64_b32 v[64:65], v73 offset0:18 offset1:19
	ds_read2st64_b32 v[66:67], v74 offset0:20 offset1:21
	ds_read2st64_b32 v[96:97], v75 offset0:22 offset1:23
	ds_read2st64_b32 v[98:99], v76 offset0:24 offset1:25
	ds_read2st64_b32 v[100:101], v77 offset0:26 offset1:27
	ds_read2st64_b32 v[102:103], v79 offset0:28 offset1:29
	ds_read2st64_b32 v[104:105], v80 offset0:30 offset1:31
	ds_read2st64_b32 v[106:107], v81 offset0:32 offset1:33
	ds_read2st64_b32 v[108:109], v82 offset0:34 offset1:35
	ds_read2st64_b32 v[110:111], v83 offset0:36 offset1:37
	ds_read2st64_b32 v[112:113], v84 offset0:38 offset1:39
	ds_read2st64_b32 v[114:115], v85 offset0:40 offset1:41
	ds_read2st64_b32 v[116:117], v86 offset0:42 offset1:43
	s_waitcnt lgkmcnt(14)
	v_add_f32_e32 v8, v118, v8
	v_add_f32_e32 v9, v60, v9
	v_cvt_pk_bf16_f32 v60, v8, v9
	v_fma_f32 v61, v7, v8, v11
	v_fma_f32 v10, v6, v8, v10
	v_fma_f32 v10, -v7, v9, v10
	v_fma_f32 v8, v6, v9, v61
	v_cvt_pk_bf16_f32 v9, v10, v8
	ds_write2_b32 v87, v60, v9 offset0:64 offset1:132
	s_waitcnt lgkmcnt(14)
	v_fma_f32 v9, -v8, v7, v62
	v_fma_f32 v8, v8, v6, v63
	v_fma_f32 v8, v10, v7, v8
	v_fma_f32 v9, v10, v6, v9
	v_cvt_pk_bf16_f32 v10, v9, v8
	s_waitcnt lgkmcnt(13)
	v_fma_f32 v11, -v8, v7, v64
	v_fma_f32 v8, v8, v6, v65
	v_fma_f32 v8, v9, v7, v8
	v_fma_f32 v11, v9, v6, v11
	v_cvt_pk_bf16_f32 v9, v11, v8
	ds_write2_b32 v88, v10, v9 offset0:72 offset1:140
	s_waitcnt lgkmcnt(13)
	v_fma_f32 v10, v7, v11, v67
	v_fma_f32 v9, v6, v11, v66
	v_fma_f32 v9, -v7, v8, v9
	v_fma_f32 v8, v6, v8, v10
	v_cvt_pk_bf16_f32 v10, v9, v8
	s_waitcnt lgkmcnt(12)
	v_fma_f32 v11, -v8, v7, v96
	v_fma_f32 v8, v8, v6, v97
	v_fma_f32 v8, v9, v7, v8
	v_fma_f32 v11, v9, v6, v11
	v_cvt_pk_bf16_f32 v9, v11, v8
	ds_write2_b32 v89, v10, v9 offset0:80 offset1:148
	s_waitcnt lgkmcnt(12)
	v_fma_f32 v10, v7, v11, v99
	v_fma_f32 v9, v6, v11, v98
	v_fma_f32 v9, -v7, v8, v9
	v_fma_f32 v8, v6, v8, v10
	v_cvt_pk_bf16_f32 v10, v9, v8
	s_waitcnt lgkmcnt(11)
	v_fma_f32 v11, -v8, v7, v100
	v_fma_f32 v8, v8, v6, v101
	v_fma_f32 v8, v9, v7, v8
	v_fma_f32 v11, v9, v6, v11
	v_cvt_pk_bf16_f32 v9, v11, v8
	ds_write2_b32 v90, v10, v9 offset0:88 offset1:156
	s_waitcnt lgkmcnt(11)
	v_fma_f32 v10, v7, v11, v103
	v_fma_f32 v9, v6, v11, v102
	v_fma_f32 v9, -v7, v8, v9
	v_fma_f32 v8, v6, v8, v10
	v_cvt_pk_bf16_f32 v10, v9, v8
	s_waitcnt lgkmcnt(10)
	v_fma_f32 v11, -v8, v7, v104
	v_fma_f32 v8, v8, v6, v105
	v_fma_f32 v8, v9, v7, v8
	v_fma_f32 v11, v9, v6, v11
	v_cvt_pk_bf16_f32 v9, v11, v8
	ds_write2_b32 v91, v10, v9 offset0:96 offset1:164
	s_waitcnt lgkmcnt(10)
	v_fma_f32 v10, v7, v11, v107
	v_fma_f32 v9, v6, v11, v106
	v_fma_f32 v9, -v7, v8, v9
	v_fma_f32 v8, v6, v8, v10
	v_cvt_pk_bf16_f32 v10, v9, v8
	s_waitcnt lgkmcnt(9)
	v_fma_f32 v11, -v8, v7, v108
	v_fma_f32 v8, v8, v6, v109
	v_fma_f32 v8, v9, v7, v8
	v_fma_f32 v11, v9, v6, v11
	v_cvt_pk_bf16_f32 v9, v11, v8
	ds_write2_b32 v92, v10, v9 offset0:104 offset1:172
	s_waitcnt lgkmcnt(9)
	v_fma_f32 v10, v7, v11, v111
	v_fma_f32 v9, v6, v11, v110
	v_fma_f32 v9, -v7, v8, v9
	v_fma_f32 v8, v6, v8, v10
	v_cvt_pk_bf16_f32 v10, v9, v8
	s_waitcnt lgkmcnt(8)
	v_fma_f32 v11, -v8, v7, v112
	v_fma_f32 v8, v8, v6, v113
	v_fma_f32 v8, v9, v7, v8
	v_fma_f32 v11, v9, v6, v11
	v_cvt_pk_bf16_f32 v9, v11, v8
	ds_write2_b32 v93, v10, v9 offset0:112 offset1:180
	s_waitcnt lgkmcnt(8)
	v_fma_f32 v10, v7, v11, v115
	v_fma_f32 v9, v6, v11, v114
	v_fma_f32 v9, -v7, v8, v9
	v_fma_f32 v8, v6, v8, v10
	v_cvt_pk_bf16_f32 v10, v9, v8
	s_waitcnt lgkmcnt(7)
	v_fma_f32 v11, v7, v9, v117
	v_fma_f32 v65, v6, v9, v116
	v_fma_f32 v65, -v7, v8, v65
	v_fma_f32 v66, v6, v8, v11
	v_cvt_pk_bf16_f32 v8, v65, v66
	ds_write2_b32 v94, v10, v8 offset0:120 offset1:188
	s_waitcnt lgkmcnt(0)
	ds_read_b128 v[8:11], v0 offset:11520
	ds_read_b128 v[60:63], v0 offset:11584
	s_waitcnt lgkmcnt(1)
	v_mfma_f32_16x16x32_bf16 v[8:11], v[8:11], v[24:27], 0
	ds_read_b128 v[96:99], v0 offset:11648
	v_mov_b32_e32 v64, 0
	s_waitcnt lgkmcnt(1)
	v_mfma_f32_16x16x32_bf16 v[8:11], v[60:63], v[20:23], v[8:11]
	ds_read_b128 v[60:63], v0 offset:11712
	s_waitcnt lgkmcnt(1)
	v_mfma_f32_16x16x32_bf16 v[8:11], v[96:99], v[16:19], v[8:11]
	s_waitcnt lgkmcnt(0)
	v_mfma_f32_16x16x32_bf16 v[8:11], v[60:63], v[12:15], v[8:11]
	v_mov_b32_e32 v60, 0
	v_mov_b32_e32 v61, 0
	v_mov_b32_e32 v62, 0
	v_mov_b32_e32 v63, 0
	s_and_saveexec_b64 s[8:9], vcc
	ds_read_b128 v[60:63], v95 offset:1536
	s_or_b64 exec, exec, s[8:9]
	s_waitcnt lgkmcnt(0)
	v_mfma_f32_16x16x32_bf16 v[96:99], v[60:63], v[52:55], 0
	v_mul_f32_e32 v67, v7, v66
	v_fma_f32 v67, v6, v65, -v67
	v_mul_f32_e32 v65, v7, v65
	v_mfma_f32_16x16x32_bf16 v[100:103], v[60:63], v[56:59], 0
	s_nop 7
	ds_write2_b32 v68, v96, v100 offset1:16
	ds_write2_b32 v68, v97, v101 offset0:132 offset1:148
	ds_write2_b32 v69, v98, v102 offset0:8 offset1:24
	v_mfma_f32_16x16x32_bf16 v[104:107], v[60:63], v[44:47], 0
	v_fmac_f32_e32 v65, v6, v66
	v_mfma_f32_16x16x32_bf16 v[108:111], v[60:63], v[48:51], 0
	ds_write2_b32 v69, v99, v103 offset0:140 offset1:156
	s_nop 6
	ds_write2_b32 v68, v104, v108 offset0:32 offset1:48
	ds_write2_b32 v68, v105, v109 offset0:164 offset1:180
	v_mfma_f32_16x16x32_bf16 v[112:115], v[60:63], v[40:43], 0
	v_mfma_f32_16x16x32_bf16 v[96:99], v[60:63], v[36:39], 0
	ds_write2_b32 v69, v106, v110 offset0:40 offset1:56
	ds_write2_b32 v69, v107, v111 offset0:172 offset1:188
	s_nop 5
	ds_write2_b32 v68, v112, v96 offset0:64 offset1:80
	ds_write2_b32 v68, v113, v97 offset0:196 offset1:212
	ds_write2_b32 v69, v114, v98 offset0:72 offset1:88
	ds_write2_b32 v69, v115, v99 offset0:204 offset1:220
	v_mfma_f32_16x16x32_bf16 v[100:103], v[60:63], v[32:35], 0
	v_mfma_f32_16x16x32_bf16 v[60:63], v[60:63], v[28:31], 0
	s_nop 7
	ds_write2_b32 v68, v100, v60 offset0:96 offset1:112
	ds_write2_b32 v68, v101, v61 offset0:228 offset1:244
	ds_write2_b32 v69, v102, v62 offset0:104 offset1:120
	ds_write2_b32 v69, v103, v63 offset0:236 offset1:252
	s_waitcnt lgkmcnt(0)
	ds_read2st64_b32 v[60:61], v70 offset0:12 offset1:13
	ds_read2st64_b32 v[62:63], v71 offset0:14 offset1:15
	ds_read2st64_b32 v[96:97], v72 offset0:16 offset1:17
	ds_read2st64_b32 v[98:99], v73 offset0:18 offset1:19
	ds_read2st64_b32 v[100:101], v74 offset0:20 offset1:21
	ds_read2st64_b32 v[102:103], v75 offset0:22 offset1:23
	ds_read2st64_b32 v[104:105], v76 offset0:24 offset1:25
	ds_read2st64_b32 v[106:107], v77 offset0:26 offset1:27
	ds_read2st64_b32 v[108:109], v79 offset0:28 offset1:29
	ds_read2st64_b32 v[110:111], v80 offset0:30 offset1:31
	ds_read2st64_b32 v[112:113], v81 offset0:32 offset1:33
	ds_read2st64_b32 v[114:115], v82 offset0:34 offset1:35
	ds_read2st64_b32 v[116:117], v83 offset0:36 offset1:37
	ds_read2st64_b32 v[118:119], v84 offset0:38 offset1:39
	ds_read2st64_b32 v[120:121], v85 offset0:40 offset1:41
	ds_read2st64_b32 v[122:123], v86 offset0:42 offset1:43
	s_waitcnt lgkmcnt(14)
	v_add_f32_e32 v60, v67, v60
	v_add_f32_e32 v61, v65, v61
	v_cvt_pk_bf16_f32 v65, v60, v61
	v_fma_f32 v66, v7, v60, v63
	v_fma_f32 v62, v6, v60, v62
	v_fma_f32 v62, -v7, v61, v62
	v_fma_f32 v60, v6, v61, v66
	v_cvt_pk_bf16_f32 v61, v62, v60
	ds_write2_b32 v87, v65, v61 offset0:64 offset1:132
	s_waitcnt lgkmcnt(14)
	v_fma_f32 v61, -v60, v7, v96
	v_fma_f32 v60, v60, v6, v97
	v_fma_f32 v60, v62, v7, v60
	v_fma_f32 v61, v62, v6, v61
	v_cvt_pk_bf16_f32 v62, v61, v60
	s_waitcnt lgkmcnt(13)
	v_fma_f32 v63, -v60, v7, v98
	v_fma_f32 v60, v60, v6, v99
	v_fma_f32 v60, v61, v7, v60
	v_fma_f32 v63, v61, v6, v63
	v_cvt_pk_bf16_f32 v61, v63, v60
	ds_write2_b32 v88, v62, v61 offset0:72 offset1:140
	s_waitcnt lgkmcnt(13)
	v_fma_f32 v62, v7, v63, v101
	v_fma_f32 v61, v6, v63, v100
	v_fma_f32 v61, -v7, v60, v61
	v_fma_f32 v60, v6, v60, v62
	v_cvt_pk_bf16_f32 v62, v61, v60
	s_waitcnt lgkmcnt(12)
	v_fma_f32 v63, -v60, v7, v102
	v_fma_f32 v60, v60, v6, v103
	v_fma_f32 v60, v61, v7, v60
	v_fma_f32 v63, v61, v6, v63
	v_cvt_pk_bf16_f32 v61, v63, v60
	ds_write2_b32 v89, v62, v61 offset0:80 offset1:148
	s_waitcnt lgkmcnt(12)
	v_fma_f32 v62, v7, v63, v105
	v_fma_f32 v61, v6, v63, v104
	v_fma_f32 v61, -v7, v60, v61
	v_fma_f32 v60, v6, v60, v62
	v_cvt_pk_bf16_f32 v62, v61, v60
	s_waitcnt lgkmcnt(11)
	v_fma_f32 v63, -v60, v7, v106
	v_fma_f32 v60, v60, v6, v107
	v_fma_f32 v60, v61, v7, v60
	v_fma_f32 v63, v61, v6, v63
	v_cvt_pk_bf16_f32 v61, v63, v60
	ds_write2_b32 v90, v62, v61 offset0:88 offset1:156
	s_waitcnt lgkmcnt(11)
	v_fma_f32 v62, v7, v63, v109
	v_fma_f32 v61, v6, v63, v108
	v_fma_f32 v61, -v7, v60, v61
	v_fma_f32 v60, v6, v60, v62
	v_cvt_pk_bf16_f32 v62, v61, v60
	s_waitcnt lgkmcnt(10)
	v_fma_f32 v63, -v60, v7, v110
	v_fma_f32 v60, v60, v6, v111
	v_fma_f32 v60, v61, v7, v60
	v_fma_f32 v63, v61, v6, v63
	v_cvt_pk_bf16_f32 v61, v63, v60
	ds_write2_b32 v91, v62, v61 offset0:96 offset1:164
	s_waitcnt lgkmcnt(10)
	v_fma_f32 v62, v7, v63, v113
	v_fma_f32 v61, v6, v63, v112
	v_fma_f32 v61, -v7, v60, v61
	v_fma_f32 v60, v6, v60, v62
	v_cvt_pk_bf16_f32 v62, v61, v60
	s_waitcnt lgkmcnt(9)
	v_fma_f32 v63, -v60, v7, v114
	v_fma_f32 v60, v60, v6, v115
	v_fma_f32 v60, v61, v7, v60
	v_fma_f32 v63, v61, v6, v63
	v_cvt_pk_bf16_f32 v61, v63, v60
	ds_write2_b32 v92, v62, v61 offset0:104 offset1:172
	s_waitcnt lgkmcnt(9)
	v_fma_f32 v62, v7, v63, v117
	v_fma_f32 v61, v6, v63, v116
	v_fma_f32 v61, -v7, v60, v61
	v_fma_f32 v60, v6, v60, v62
	v_cvt_pk_bf16_f32 v62, v61, v60
	s_waitcnt lgkmcnt(8)
	v_fma_f32 v63, -v60, v7, v118
	v_fma_f32 v60, v60, v6, v119
	v_fma_f32 v60, v61, v7, v60
	v_fma_f32 v63, v61, v6, v63
	v_cvt_pk_bf16_f32 v61, v63, v60
	ds_write2_b32 v93, v62, v61 offset0:112 offset1:180
	s_waitcnt lgkmcnt(8)
	v_fma_f32 v62, v7, v63, v121
	v_fma_f32 v61, v6, v63, v120
	v_fma_f32 v61, -v7, v60, v61
	v_fma_f32 v60, v6, v60, v62
	v_cvt_pk_bf16_f32 v62, v61, v60
	s_waitcnt lgkmcnt(7)
	v_fma_f32 v63, v7, v61, v123
	v_fma_f32 v96, v6, v61, v122
	v_fma_f32 v96, -v7, v60, v96
	v_fma_f32 v97, v6, v60, v63
	v_cvt_pk_bf16_f32 v60, v96, v97
	ds_write2_b32 v94, v62, v60 offset0:120 offset1:188
	s_waitcnt lgkmcnt(0)
	ds_read_b128 v[60:63], v0 offset:11520
	ds_read_b128 v[98:101], v0 offset:11584
	s_waitcnt lgkmcnt(1)
	v_mfma_f32_16x16x32_bf16 v[60:63], v[60:63], v[24:27], 0
	ds_read_b128 v[102:105], v0 offset:11648
	v_mov_b32_e32 v65, 0
	v_mov_b32_e32 v66, 0
	s_waitcnt lgkmcnt(1)
	v_mfma_f32_16x16x32_bf16 v[60:63], v[98:101], v[20:23], v[60:63]
	ds_read_b128 v[98:101], v0 offset:11712
	v_mov_b32_e32 v67, 0
	s_waitcnt lgkmcnt(1)
	v_mfma_f32_16x16x32_bf16 v[60:63], v[102:105], v[16:19], v[60:63]
	s_waitcnt lgkmcnt(0)
	v_mfma_f32_16x16x32_bf16 v[60:63], v[98:101], v[12:15], v[60:63]
	s_and_saveexec_b64 s[8:9], vcc
	ds_read_b128 v[64:67], v95 offset:2304
	s_or_b64 exec, exec, s[8:9]
	s_waitcnt lgkmcnt(0)
	v_mfma_f32_16x16x32_bf16 v[52:55], v[64:67], v[52:55], 0
	s_mov_b32 s9, 0x200000
	v_mfma_f32_16x16x32_bf16 v[56:59], v[64:67], v[56:59], 0
	s_nop 7
	ds_write2_b32 v68, v52, v56 offset1:16
	ds_write2_b32 v68, v53, v57 offset0:132 offset1:148
	ds_write2_b32 v69, v54, v58 offset0:8 offset1:24
	ds_write2_b32 v69, v55, v59 offset0:140 offset1:156
	v_mfma_f32_16x16x32_bf16 v[44:47], v[64:67], v[44:47], 0
	v_mfma_f32_16x16x32_bf16 v[48:51], v[64:67], v[48:51], 0
	s_nop 7
	ds_write2_b32 v68, v44, v48 offset0:32 offset1:48
	ds_write2_b32 v68, v45, v49 offset0:164 offset1:180
	ds_write2_b32 v69, v46, v50 offset0:40 offset1:56
	ds_write2_b32 v69, v47, v51 offset0:172 offset1:188
	v_mfma_f32_16x16x32_bf16 v[40:43], v[64:67], v[40:43], 0
	v_mfma_f32_16x16x32_bf16 v[36:39], v[64:67], v[36:39], 0
	s_nop 7
	ds_write2_b32 v68, v40, v36 offset0:64 offset1:80
	ds_write2_b32 v68, v41, v37 offset0:196 offset1:212
	ds_write2_b32 v69, v42, v38 offset0:72 offset1:88
	ds_write2_b32 v69, v43, v39 offset0:204 offset1:220
	v_mfma_f32_16x16x32_bf16 v[32:35], v[64:67], v[32:35], 0
	v_mfma_f32_16x16x32_bf16 v[28:31], v[64:67], v[28:31], 0
	s_nop 7
	ds_write2_b32 v68, v32, v28 offset0:96 offset1:112
	ds_write2_b32 v68, v33, v29 offset0:228 offset1:244
	ds_write2_b32 v69, v34, v30 offset0:104 offset1:120
	ds_write2_b32 v69, v35, v31 offset0:236 offset1:252
	s_waitcnt lgkmcnt(0)
	v_mul_f32_e32 v64, v7, v97
	ds_read2st64_b32 v[28:29], v70 offset0:12 offset1:13
	ds_read2st64_b32 v[30:31], v71 offset0:14 offset1:15
	ds_read2st64_b32 v[32:33], v72 offset0:16 offset1:17
	ds_read2st64_b32 v[34:35], v73 offset0:18 offset1:19
	ds_read2st64_b32 v[36:37], v74 offset0:20 offset1:21
	ds_read2st64_b32 v[38:39], v75 offset0:22 offset1:23
	ds_read2st64_b32 v[40:41], v76 offset0:24 offset1:25
	ds_read2st64_b32 v[42:43], v77 offset0:26 offset1:27
	ds_read2st64_b32 v[44:45], v79 offset0:28 offset1:29
	ds_read2st64_b32 v[46:47], v80 offset0:30 offset1:31
	ds_read2st64_b32 v[48:49], v81 offset0:32 offset1:33
	ds_read2st64_b32 v[50:51], v82 offset0:34 offset1:35
	ds_read2st64_b32 v[52:53], v83 offset0:36 offset1:37
	ds_read2st64_b32 v[54:55], v84 offset0:38 offset1:39
	ds_read2st64_b32 v[56:57], v85 offset0:40 offset1:41
	ds_read2st64_b32 v[58:59], v86 offset0:42 offset1:43
	v_fma_f32 v64, v6, v96, -v64
	s_waitcnt lgkmcnt(14)
	v_add_f32_e32 v28, v64, v28
	v_mul_f32_e32 v64, v7, v96
	v_fmac_f32_e32 v64, v6, v97
	v_add_f32_e32 v29, v64, v29
	v_cvt_pk_bf16_f32 v64, v28, v29
	v_fma_f32 v65, v7, v28, v31
	v_fma_f32 v30, v6, v28, v30
	v_fma_f32 v30, -v7, v29, v30
	v_fma_f32 v28, v6, v29, v65
	v_cvt_pk_bf16_f32 v29, v30, v28
	ds_write2_b32 v87, v64, v29 offset0:64 offset1:132
	s_waitcnt lgkmcnt(14)
	v_fma_f32 v29, -v28, v7, v32
	v_fma_f32 v28, v28, v6, v33
	v_fma_f32 v28, v30, v7, v28
	v_fma_f32 v29, v30, v6, v29
	v_cvt_pk_bf16_f32 v30, v29, v28
	s_waitcnt lgkmcnt(13)
	v_fma_f32 v31, -v28, v7, v34
	v_fma_f32 v28, v28, v6, v35
	v_fma_f32 v28, v29, v7, v28
	v_fma_f32 v31, v29, v6, v31
	v_cvt_pk_bf16_f32 v29, v31, v28
	ds_write2_b32 v88, v30, v29 offset0:72 offset1:140
	s_waitcnt lgkmcnt(13)
	v_fma_f32 v30, v7, v31, v37
	v_fma_f32 v29, v6, v31, v36
	v_fma_f32 v29, -v7, v28, v29
	v_fma_f32 v28, v6, v28, v30
	v_cvt_pk_bf16_f32 v30, v29, v28
	s_waitcnt lgkmcnt(12)
	v_fma_f32 v31, -v28, v7, v38
	v_fma_f32 v28, v28, v6, v39
	v_fma_f32 v28, v29, v7, v28
	v_fma_f32 v31, v29, v6, v31
	v_cvt_pk_bf16_f32 v29, v31, v28
	ds_write2_b32 v89, v30, v29 offset0:80 offset1:148
	s_waitcnt lgkmcnt(12)
	v_fma_f32 v30, v7, v31, v41
	v_fma_f32 v29, v6, v31, v40
	v_fma_f32 v29, -v7, v28, v29
	v_fma_f32 v28, v6, v28, v30
	v_cvt_pk_bf16_f32 v30, v29, v28
	s_waitcnt lgkmcnt(11)
	v_fma_f32 v31, -v28, v7, v42
	v_fma_f32 v28, v28, v6, v43
	v_fma_f32 v28, v29, v7, v28
	v_fma_f32 v31, v29, v6, v31
	v_cvt_pk_bf16_f32 v29, v31, v28
	ds_write2_b32 v90, v30, v29 offset0:88 offset1:156
	s_waitcnt lgkmcnt(11)
	v_fma_f32 v30, v7, v31, v45
	v_fma_f32 v29, v6, v31, v44
	v_fma_f32 v29, -v7, v28, v29
	v_fma_f32 v28, v6, v28, v30
	v_cvt_pk_bf16_f32 v30, v29, v28
	s_waitcnt lgkmcnt(10)
	v_fma_f32 v31, -v28, v7, v46
	v_fma_f32 v28, v28, v6, v47
	v_fma_f32 v28, v29, v7, v28
	v_fma_f32 v31, v29, v6, v31
	v_cvt_pk_bf16_f32 v29, v31, v28
	ds_write2_b32 v91, v30, v29 offset0:96 offset1:164
	s_waitcnt lgkmcnt(10)
	v_fma_f32 v30, v7, v31, v49
	v_fma_f32 v29, v6, v31, v48
	v_fma_f32 v29, -v7, v28, v29
	v_fma_f32 v28, v6, v28, v30
	v_cvt_pk_bf16_f32 v30, v29, v28
	s_waitcnt lgkmcnt(9)
	v_fma_f32 v31, -v28, v7, v50
	v_fma_f32 v28, v28, v6, v51
	v_fma_f32 v28, v29, v7, v28
	v_fma_f32 v31, v29, v6, v31
	v_cvt_pk_bf16_f32 v29, v31, v28
	ds_write2_b32 v92, v30, v29 offset0:104 offset1:172
	s_waitcnt lgkmcnt(9)
	v_fma_f32 v30, v7, v31, v53
	v_fma_f32 v29, v6, v31, v52
	v_fma_f32 v29, -v7, v28, v29
	v_fma_f32 v28, v6, v28, v30
	v_cvt_pk_bf16_f32 v30, v29, v28
	s_waitcnt lgkmcnt(8)
	v_fma_f32 v31, -v28, v7, v54
	v_fma_f32 v28, v28, v6, v55
	v_fma_f32 v28, v29, v7, v28
	v_fma_f32 v31, v29, v6, v31
	v_cvt_pk_bf16_f32 v29, v31, v28
	ds_write2_b32 v93, v30, v29 offset0:112 offset1:180
	s_waitcnt lgkmcnt(8)
	v_fma_f32 v30, v7, v31, v57
	v_fma_f32 v29, v6, v31, v56
	v_fma_f32 v29, -v7, v28, v29
	v_fma_f32 v28, v6, v28, v30
	v_mul_f32_e32 v31, v7, v28
	v_mul_f32_e32 v7, v7, v29
	v_fma_f32 v31, v6, v29, -v31
	v_fmac_f32_e32 v7, v6, v28
	s_waitcnt lgkmcnt(7)
	v_add_f32_e32 v31, v58, v31
	v_add_f32_e32 v6, v59, v7
	v_cvt_pk_bf16_f32 v30, v29, v28
	v_cvt_pk_bf16_f32 v6, v31, v6
	ds_write2_b32 v94, v30, v6 offset0:120 offset1:188
	s_waitcnt lgkmcnt(0)
	ds_read_b128 v[28:31], v0 offset:11520
	s_waitcnt lgkmcnt(0)
	v_mfma_f32_16x16x32_bf16 v[24:27], v[28:31], v[24:27], 0
	ds_read_b128 v[28:31], v0 offset:11584
	v_mov_b32_e32 v73, v204
	v_mov_b32_e32 v72, 0
	s_waitcnt lgkmcnt(0)
	v_mfma_f32_16x16x32_bf16 v[20:23], v[28:31], v[20:23], v[24:27]
	s_nop 2
	ds_read_b128 v[24:27], v0 offset:11648
	v_mov_b32_e32 v75, 0
	v_mov_b32_e32 v76, 0
	s_waitcnt lgkmcnt(0)
	v_mfma_f32_16x16x32_bf16 v[16:19], v[24:27], v[16:19], v[20:23]
	s_nop 2
	ds_read_b128 v[20:23], v0 offset:11712
	v_mov_b32_e32 v0, s59
	ds_read_b64 v[6:7], v0
	v_readfirstlane_b32 s5, v73
	s_lshr_b32 s5, s5, 6
	s_mulk_i32 s5, 0x3e00
	s_add_i32 s8, s5, 0
	v_readlane_b32 s5, v244, 25
	v_and_b32_e32 v59, 63, v73
	s_add_i32 s28, s4, s5
	s_waitcnt lgkmcnt(0)
	v_readfirstlane_b32 s4, v6
	v_lshl_or_b32 v6, s28, 6, v59
	v_readfirstlane_b32 s5, v7
	v_ashrrev_i32_e32 v7, 31, v6
	s_ashr_i32 s29, s28, 31
	v_lshl_add_u64 v[6:7], v[6:7], 4, s[4:5]
	s_lshl_b64 s[38:39], s[28:29], 13
	v_add_co_u32_e32 v6, vcc, s9, v6
	s_add_u32 s38, s4, s38
	v_and_b32_e32 v58, 15, v73
	v_addc_co_u32_e32 v7, vcc, 0, v7, vcc
	s_addc_u32 s39, s5, s39
	v_and_b32_e32 v0, 48, v73
	v_mfma_f32_16x16x32_bf16 v[12:15], v[20:23], v[12:15], v[16:19]
	global_load_dwordx2 v[32:33], v[6:7], off
	v_lshl_add_u64 v[6:7], s[38:39], 0, v[0:1]
	s_mov_b32 s9, 0x240000
	v_lshlrev_b32_e32 v16, 6, v58
	v_mov_b32_e32 v17, v1
	v_lshl_add_u64 v[6:7], v[6:7], 0, v[16:17]
	v_add_co_u32_e32 v18, vcc, s9, v6
	s_mov_b64 s[38:39], 0x240000
	s_nop 0
	v_addc_co_u32_e32 v19, vcc, 0, v7, vcc
	s_mov_b32 s9, 0x241000
	v_lshl_add_u64 v[16:17], v[6:7], 0, s[38:39]
	v_add_co_u32_e32 v6, vcc, s9, v6
	s_lshl_b64 s[28:29], s[28:29], 12
	s_nop 0
	v_addc_co_u32_e32 v7, vcc, 0, v7, vcc
	s_add_u32 s28, s4, s28
	global_load_dwordx4 v[42:45], v[18:19], off
	global_load_dwordx4 v[68:71], v[16:17], off offset:1024
	global_load_dwordx4 v[64:67], v[16:17], off offset:2048
	global_load_dwordx4 v[50:53], v[16:17], off offset:3072
	global_load_dwordx4 v[54:57], v[6:7], off
	global_load_dwordx4 v[46:49], v[6:7], off offset:1024
	global_load_dwordx4 v[38:41], v[6:7], off offset:2048
	s_waitcnt lgkmcnt(0)
	global_load_dwordx4 v[34:37], v[6:7], off offset:3072
	s_addc_u32 s29, s5, s29
	v_lshlrev_b32_e32 v6, 8, v58
	v_mov_b32_e32 v7, v1
	v_lshl_add_u64 v[6:7], s[28:29], 0, v[6:7]
	v_lshl_add_u64 v[6:7], v[6:7], 0, v[0:1]
	s_mov_b64 s[28:29], 0x380000
	s_mov_b32 s9, 0x380000
	v_lshl_add_u64 v[16:17], v[6:7], 0, s[28:29]
	v_add_co_u32_e32 v6, vcc, s9, v6
	s_or_b32 s9, s26, 1
	s_mul_hi_i32 s28, s9, 0x44
	s_mulk_i32 s9, 0x44
	s_add_u32 s26, s9, s22
	s_addc_u32 s27, s28, s27
	s_lshl_b64 s[26:27], s[26:27], 10
	s_add_u32 s6, s26, s6
	v_addc_co_u32_e32 v7, vcc, 0, v7, vcc
	s_addc_u32 s7, s27, s7
	global_load_dwordx4 v[20:23], v[6:7], off
	global_load_dwordx4 v[28:31], v[16:17], off offset:64
	global_load_dwordx4 v[24:27], v[16:17], off offset:128
	s_nop 0
	global_load_dwordx4 v[16:19], v[16:17], off offset:192
	v_or_b32_e32 v6, s6, v59
	v_mov_b32_e32 v7, s7
	v_lshl_add_u64 v[6:7], v[6:7], 3, s[4:5]
	v_add_co_u32_e32 v6, vcc, 0x1500000, v6
	v_add_u32_e32 v74, s8, v0
	s_nop 0
	v_addc_co_u32_e32 v7, vcc, 0, v7, vcc
	global_load_dwordx2 v[6:7], v[6:7], off
	v_cmp_gt_u32_e32 vcc, 32, v59
	v_mad_u32_u24 v81, v58, 48, v74
	v_mov_b32_e32 v74, 0
	v_mov_b32_e32 v77, 0
	s_and_saveexec_b64 s[4:5], vcc
	ds_read_b128 v[74:77], v81 offset:2304
	s_or_b64 exec, exec, s[4:5]
	s_waitcnt vmcnt(6) lgkmcnt(0)
	v_mfma_f32_16x16x32_bf16 v[82:85], v[74:77], v[42:45], 0
	v_bfe_u32 v73, v73, 4, 2
	v_mov_b32_e32 v80, s8
	s_movk_i32 s4, 0x110
	v_mfma_f32_16x16x32_bf16 v[86:89], v[74:77], v[68:71], 0
	v_lshlrev_b32_e32 v79, 2, v58
	v_mad_u32_u24 v126, v58, s4, v80
	v_mul_u32_u24_e32 v58, 0x840, v73
	v_mfma_f32_16x16x32_bf16 v[90:93], v[74:77], v[64:67], 0
	v_add3_u32 v58, s8, v79, v58
	v_add_u32_e32 v80, 0xc00, v58
	s_nop 1
	ds_write2_b32 v80, v82, v86 offset1:16
	v_mfma_f32_16x16x32_bf16 v[94:97], v[74:77], v[50:53], 0
	v_add_u32_e32 v82, 0x1000, v58
	ds_write2_b32 v80, v83, v87 offset0:132 offset1:148
	ds_write2_b32 v82, v84, v88 offset0:8 offset1:24
	v_mfma_f32_16x16x32_bf16 v[98:101], v[74:77], v[54:57], 0
	ds_write2_b32 v82, v85, v89 offset0:140 offset1:156
	s_nop 2
	ds_write2_b32 v80, v90, v94 offset0:32 offset1:48
	ds_write2_b32 v80, v91, v95 offset0:164 offset1:180
	v_lshlrev_b32_e32 v59, 2, v59
	v_add_u32_e32 v83, s8, v59
	v_mfma_f32_16x16x32_bf16 v[84:87], v[74:77], v[46:49], 0
	ds_write2_b32 v82, v92, v96 offset0:40 offset1:56
	ds_write2_b32 v82, v93, v97 offset0:172 offset1:188
	s_nop 5
	ds_write2_b32 v80, v98, v84 offset0:64 offset1:80
	ds_write2_b32 v80, v99, v85 offset0:196 offset1:212
	ds_write2_b32 v82, v100, v86 offset0:72 offset1:88
	ds_write2_b32 v82, v101, v87 offset0:204 offset1:220
	v_mfma_f32_16x16x32_bf16 v[88:91], v[74:77], v[38:41], 0
	v_add_u32_e32 v84, 0xf0, v83
	v_add_u32_e32 v85, 0xe0, v83
	s_waitcnt vmcnt(0)
	v_mul_f32_e32 v73, v33, v7
	v_mfma_f32_16x16x32_bf16 v[74:77], v[74:77], v[34:37], 0
	s_nop 7
	ds_write2_b32 v80, v88, v74 offset0:96 offset1:112
	ds_write2_b32 v80, v89, v75 offset0:228 offset1:244
	ds_write2_b32 v82, v90, v76 offset0:104 offset1:120
	ds_write2_b32 v82, v91, v77 offset0:236 offset1:252
	s_waitcnt lgkmcnt(0)
	ds_read2st64_b32 v[58:59], v84 offset0:42 offset1:43
	ds_read2st64_b32 v[74:75], v85 offset0:40 offset1:41
	v_fma_f32 v73, v32, v6, -v73
	v_mul_f32_e32 v6, v33, v6
	v_fmac_f32_e32 v6, v32, v7
	s_waitcnt lgkmcnt(1)
	v_add_f32_e32 v58, v73, v58
	v_add_f32_e32 v6, v6, v59
	v_add_u32_e32 v86, 0xd0, v83
	v_cvt_pk_bf16_f32 v7, v58, v6
	ds_read2st64_b32 v[76:77], v86 offset0:38 offset1:39
	s_waitcnt lgkmcnt(1)
	v_fma_f32 v59, -v6, v33, v74
	v_fma_f32 v6, v6, v32, v75
	v_fma_f32 v6, v58, v33, v6
	v_fma_f32 v59, v58, v32, v59
	v_add_u32_e32 v87, 0xc0, v83
	v_add_u32_e32 v88, 0xb0, v83
	v_add_u32_e32 v89, 0xa0, v83
	v_add_u32_e32 v90, 0x90, v83
	v_add_u32_e32 v91, 0x80, v83
	v_add_u32_e32 v92, 0x70, v83
	v_add_u32_e32 v93, 0x60, v83
	v_add_u32_e32 v94, 0x50, v83
	v_add_u32_e32 v95, 64, v83
	v_add_u32_e32 v96, 48, v83
	v_add_u32_e32 v97, 32, v83
	v_add_u32_e32 v98, 16, v83
	v_cvt_pk_bf16_f32 v58, v59, v6
	v_add_u32_e32 v99, 0x3a00, v83
	ds_read2st64_b32 v[100:101], v87 offset0:36 offset1:37
	ds_read2st64_b32 v[102:103], v88 offset0:34 offset1:35
	ds_read2st64_b32 v[104:105], v89 offset0:32 offset1:33
	ds_read2st64_b32 v[106:107], v90 offset0:30 offset1:31
	ds_read2st64_b32 v[108:109], v91 offset0:28 offset1:29
	ds_read2st64_b32 v[110:111], v92 offset0:26 offset1:27
	ds_read2st64_b32 v[112:113], v93 offset0:24 offset1:25
	ds_read2st64_b32 v[114:115], v94 offset0:22 offset1:23
	ds_read2st64_b32 v[116:117], v95 offset0:20 offset1:21
	ds_read2st64_b32 v[118:119], v96 offset0:18 offset1:19
	ds_read2st64_b32 v[120:121], v97 offset0:16 offset1:17
	ds_read2st64_b32 v[122:123], v98 offset0:14 offset1:15
	ds_read2st64_b32 v[124:125], v83 offset0:12 offset1:13
	ds_write2_b32 v99, v58, v7 offset0:120 offset1:188
	s_waitcnt lgkmcnt(14)
	v_fma_f32 v58, v33, v59, v77
	v_fma_f32 v7, v32, v59, v76
	v_fma_f32 v7, -v33, v6, v7
	v_fma_f32 v6, v32, v6, v58
	v_cvt_pk_bf16_f32 v58, v7, v6
	s_waitcnt lgkmcnt(13)
	v_fma_f32 v59, -v6, v33, v100
	v_fma_f32 v6, v6, v32, v101
	v_fma_f32 v6, v7, v33, v6
	v_fma_f32 v59, v7, v32, v59
	v_cvt_pk_bf16_f32 v7, v59, v6
	v_add_u32_e32 v100, 0x3800, v83
	ds_write2_b32 v100, v7, v58 offset0:112 offset1:180
	s_waitcnt lgkmcnt(13)
	v_fma_f32 v58, v33, v59, v103
	v_fma_f32 v7, v32, v59, v102
	v_fma_f32 v7, -v33, v6, v7
	v_fma_f32 v6, v32, v6, v58
	v_cvt_pk_bf16_f32 v58, v7, v6
	s_waitcnt lgkmcnt(12)
	v_fma_f32 v59, -v6, v33, v104
	v_fma_f32 v6, v6, v32, v105
	v_fma_f32 v6, v7, v33, v6
	v_fma_f32 v59, v7, v32, v59
	v_cvt_pk_bf16_f32 v7, v59, v6
	v_add_u32_e32 v101, 0x3600, v83
	ds_write2_b32 v101, v7, v58 offset0:104 offset1:172
	s_waitcnt lgkmcnt(12)
	v_fma_f32 v58, v33, v59, v107
	v_fma_f32 v7, v32, v59, v106
	v_fma_f32 v7, -v33, v6, v7
	v_fma_f32 v6, v32, v6, v58
	v_cvt_pk_bf16_f32 v58, v7, v6
	s_waitcnt lgkmcnt(11)
	v_fma_f32 v59, -v6, v33, v108
	v_fma_f32 v6, v6, v32, v109
	v_fma_f32 v6, v7, v33, v6
	v_fma_f32 v59, v7, v32, v59
	v_cvt_pk_bf16_f32 v7, v59, v6
	v_add_u32_e32 v102, 0x3400, v83
	ds_write2_b32 v102, v7, v58 offset0:96 offset1:164
	s_waitcnt lgkmcnt(11)
	v_fma_f32 v58, v33, v59, v111
	v_fma_f32 v7, v32, v59, v110
	v_fma_f32 v7, -v33, v6, v7
	v_fma_f32 v6, v32, v6, v58
	v_cvt_pk_bf16_f32 v58, v7, v6
	s_waitcnt lgkmcnt(10)
	v_fma_f32 v59, -v6, v33, v112
	v_fma_f32 v6, v6, v32, v113
	v_fma_f32 v6, v7, v33, v6
	v_fma_f32 v59, v7, v32, v59
	v_cvt_pk_bf16_f32 v7, v59, v6
	v_add_u32_e32 v103, 0x3200, v83
	ds_write2_b32 v103, v7, v58 offset0:88 offset1:156
	s_waitcnt lgkmcnt(10)
	v_fma_f32 v58, v33, v59, v115
	v_fma_f32 v7, v32, v59, v114
	v_fma_f32 v7, -v33, v6, v7
	v_fma_f32 v6, v32, v6, v58
	v_cvt_pk_bf16_f32 v58, v7, v6
	s_waitcnt lgkmcnt(9)
	v_fma_f32 v59, -v6, v33, v116
	v_fma_f32 v6, v6, v32, v117
	v_fma_f32 v6, v7, v33, v6
	v_fma_f32 v59, v7, v32, v59
	v_cvt_pk_bf16_f32 v7, v59, v6
	v_add_u32_e32 v104, 0x3000, v83
	ds_write2_b32 v104, v7, v58 offset0:80 offset1:148
	s_waitcnt lgkmcnt(9)
	v_fma_f32 v58, v33, v59, v119
	v_fma_f32 v7, v32, v59, v118
	v_fma_f32 v7, -v33, v6, v7
	v_fma_f32 v6, v32, v6, v58
	v_cvt_pk_bf16_f32 v58, v7, v6
	s_waitcnt lgkmcnt(8)
	v_fma_f32 v59, -v6, v33, v120
	v_fma_f32 v6, v6, v32, v121
	v_fma_f32 v6, v7, v33, v6
	v_fma_f32 v59, v7, v32, v59
	v_cvt_pk_bf16_f32 v7, v59, v6
	v_add_u32_e32 v105, 0x2e00, v83
	ds_write2_b32 v105, v7, v58 offset0:72 offset1:140
	s_waitcnt lgkmcnt(8)
	v_fma_f32 v58, v33, v59, v123
	v_fma_f32 v7, v32, v59, v122
	v_fma_f32 v7, -v33, v6, v7
	v_fma_f32 v58, v32, v6, v58
	v_mul_f32_e32 v6, v33, v58
	v_cvt_pk_bf16_f32 v59, v7, v58
	v_fma_f32 v6, v32, v7, -v6
	v_mul_f32_e32 v7, v33, v7
	v_fmac_f32_e32 v7, v32, v58
	s_waitcnt lgkmcnt(7)
	v_add_f32_e32 v6, v124, v6
	v_add_f32_e32 v7, v125, v7
	v_cvt_pk_bf16_f32 v58, v6, v7
	v_add_u32_e32 v106, 0x2c00, v83
	ds_write2_b32 v106, v58, v59 offset0:64 offset1:132
	s_waitcnt lgkmcnt(0)
	v_add_u32_e32 v79, v126, v0
	ds_read_b128 v[74:77], v79 offset:11520
	ds_read_b128 v[108:111], v79 offset:11584
	s_waitcnt lgkmcnt(1)
	v_mfma_f32_16x16x32_bf16 v[12:15], v[74:77], v[20:23], v[12:15]
	ds_read_b128 v[74:77], v79 offset:11648
	v_mov_b32_e32 v73, 0
	s_waitcnt lgkmcnt(1)
	v_mfma_f32_16x16x32_bf16 v[12:15], v[108:111], v[28:31], v[12:15]
	ds_read_b128 v[108:111], v79 offset:11712
	s_waitcnt lgkmcnt(1)
	v_mfma_f32_16x16x32_bf16 v[12:15], v[74:77], v[24:27], v[12:15]
	v_mov_b32_e32 v74, 0
	v_mov_b32_e32 v75, 0
	s_waitcnt lgkmcnt(0)
	v_mfma_f32_16x16x32_bf16 v[12:15], v[108:111], v[16:19], v[12:15]
	s_and_saveexec_b64 s[4:5], vcc
	ds_read_b128 v[72:75], v81 offset:1536
	s_or_b64 exec, exec, s[4:5]
	s_waitcnt lgkmcnt(0)
	v_mfma_f32_16x16x32_bf16 v[108:111], v[72:75], v[42:45], 0
	v_mul_f32_e32 v0, v33, v7
	v_fma_f32 v0, v32, v6, -v0
	v_mul_f32_e32 v6, v33, v6
	v_mfma_f32_16x16x32_bf16 v[112:115], v[72:75], v[68:71], 0
	s_nop 7
	ds_write2_b32 v80, v108, v112 offset1:16
	ds_write2_b32 v80, v109, v113 offset0:132 offset1:148
	ds_write2_b32 v82, v110, v114 offset0:8 offset1:24
	v_mfma_f32_16x16x32_bf16 v[116:119], v[72:75], v[64:67], 0
	v_fmac_f32_e32 v6, v32, v7
	v_mfma_f32_16x16x32_bf16 v[120:123], v[72:75], v[50:53], 0
	ds_write2_b32 v82, v111, v115 offset0:140 offset1:156
	s_nop 6
	ds_write2_b32 v80, v116, v120 offset0:32 offset1:48
	ds_write2_b32 v80, v117, v121 offset0:164 offset1:180
	v_mfma_f32_16x16x32_bf16 v[124:127], v[72:75], v[54:57], 0
	v_mfma_f32_16x16x32_bf16 v[108:111], v[72:75], v[46:49], 0
	ds_write2_b32 v82, v118, v122 offset0:40 offset1:56
	ds_write2_b32 v82, v119, v123 offset0:172 offset1:188
	s_nop 5
	ds_write2_b32 v80, v124, v108 offset0:64 offset1:80
	ds_write2_b32 v80, v125, v109 offset0:196 offset1:212
	ds_write2_b32 v82, v126, v110 offset0:72 offset1:88
	ds_write2_b32 v82, v127, v111 offset0:204 offset1:220
	v_mfma_f32_16x16x32_bf16 v[112:115], v[72:75], v[38:41], 0
	v_mfma_f32_16x16x32_bf16 v[72:75], v[72:75], v[34:37], 0
	s_nop 7
	ds_write2_b32 v80, v112, v72 offset0:96 offset1:112
	ds_write2_b32 v80, v113, v73 offset0:228 offset1:244
	ds_write2_b32 v82, v114, v74 offset0:104 offset1:120
	ds_write2_b32 v82, v115, v75 offset0:236 offset1:252
	s_waitcnt lgkmcnt(0)
	ds_read2st64_b32 v[58:59], v84 offset0:42 offset1:43
	ds_read2st64_b32 v[72:73], v85 offset0:40 offset1:41
	ds_read2st64_b32 v[74:75], v86 offset0:38 offset1:39
	ds_read2st64_b32 v[76:77], v87 offset0:36 offset1:37
	ds_read2st64_b32 v[108:109], v88 offset0:34 offset1:35
	ds_read2st64_b32 v[110:111], v89 offset0:32 offset1:33
	ds_read2st64_b32 v[112:113], v90 offset0:30 offset1:31
	ds_read2st64_b32 v[114:115], v91 offset0:28 offset1:29
	ds_read2st64_b32 v[116:117], v92 offset0:26 offset1:27
	ds_read2st64_b32 v[118:119], v93 offset0:24 offset1:25
	ds_read2st64_b32 v[120:121], v94 offset0:22 offset1:23
	ds_read2st64_b32 v[122:123], v95 offset0:20 offset1:21
	ds_read2st64_b32 v[124:125], v96 offset0:18 offset1:19
	ds_read2st64_b32 v[126:127], v97 offset0:16 offset1:17
	ds_read2st64_b32 v[128:129], v98 offset0:14 offset1:15
	ds_read2st64_b32 v[130:131], v83 offset0:12 offset1:13
	s_waitcnt lgkmcnt(14)
	v_add_f32_e32 v0, v0, v58
	v_add_f32_e32 v6, v6, v59
	v_cvt_pk_bf16_f32 v7, v0, v6
	v_mul_f32_e32 v58, v33, v6
	v_mul_f32_e32 v6, v32, v6
	v_fma_f32 v58, v32, v0, -v58
	v_fmac_f32_e32 v6, v33, v0
	v_add_f32_e32 v58, v72, v58
	v_add_f32_e32 v0, v73, v6
	v_cvt_pk_bf16_f32 v6, v58, v0
	ds_write2_b32 v99, v6, v7 offset0:120 offset1:188
	s_waitcnt lgkmcnt(14)
	v_fma_f32 v7, v33, v58, v75
	v_fma_f32 v6, v32, v58, v74
	v_fma_f32 v6, -v33, v0, v6
	v_fma_f32 v0, v32, v0, v7
	v_cvt_pk_bf16_f32 v7, v6, v0
	s_waitcnt lgkmcnt(13)
	v_fma_f32 v58, -v0, v33, v76
	v_fma_f32 v0, v0, v32, v77
	v_fma_f32 v0, v6, v33, v0
	v_fma_f32 v58, v6, v32, v58
	v_cvt_pk_bf16_f32 v6, v58, v0
	ds_write2_b32 v100, v6, v7 offset0:112 offset1:180
	s_waitcnt lgkmcnt(13)
	v_fma_f32 v7, v33, v58, v109
	v_fma_f32 v6, v32, v58, v108
	v_fma_f32 v6, -v33, v0, v6
	v_fma_f32 v0, v32, v0, v7
	v_cvt_pk_bf16_f32 v7, v6, v0
	s_waitcnt lgkmcnt(12)
	v_fma_f32 v58, -v0, v33, v110
	v_fma_f32 v0, v0, v32, v111
	v_fma_f32 v0, v6, v33, v0
	v_fma_f32 v58, v6, v32, v58
	v_cvt_pk_bf16_f32 v6, v58, v0
	ds_write2_b32 v101, v6, v7 offset0:104 offset1:172
	s_waitcnt lgkmcnt(12)
	v_fma_f32 v7, v33, v58, v113
	v_fma_f32 v6, v32, v58, v112
	v_fma_f32 v6, -v33, v0, v6
	v_fma_f32 v0, v32, v0, v7
	v_cvt_pk_bf16_f32 v7, v6, v0
	s_waitcnt lgkmcnt(11)
	v_fma_f32 v58, -v0, v33, v114
	v_fma_f32 v0, v0, v32, v115
	v_fma_f32 v0, v6, v33, v0
	v_fma_f32 v58, v6, v32, v58
	v_cvt_pk_bf16_f32 v6, v58, v0
	ds_write2_b32 v102, v6, v7 offset0:96 offset1:164
	s_waitcnt lgkmcnt(11)
	v_fma_f32 v7, v33, v58, v117
	v_fma_f32 v6, v32, v58, v116
	v_fma_f32 v6, -v33, v0, v6
	v_fma_f32 v0, v32, v0, v7
	v_cvt_pk_bf16_f32 v7, v6, v0
	s_waitcnt lgkmcnt(10)
	v_fma_f32 v58, -v0, v33, v118
	v_fma_f32 v0, v0, v32, v119
	v_fma_f32 v0, v6, v33, v0
	v_fma_f32 v58, v6, v32, v58
	v_cvt_pk_bf16_f32 v6, v58, v0
	ds_write2_b32 v103, v6, v7 offset0:88 offset1:156
	s_waitcnt lgkmcnt(10)
	v_fma_f32 v7, v33, v58, v121
	v_fma_f32 v6, v32, v58, v120
	v_fma_f32 v6, -v33, v0, v6
	v_fma_f32 v0, v32, v0, v7
	v_cvt_pk_bf16_f32 v7, v6, v0
	s_waitcnt lgkmcnt(9)
	v_fma_f32 v58, -v0, v33, v122
	v_fma_f32 v0, v0, v32, v123
	v_fma_f32 v0, v6, v33, v0
	v_fma_f32 v58, v6, v32, v58
	v_cvt_pk_bf16_f32 v6, v58, v0
	ds_write2_b32 v104, v6, v7 offset0:80 offset1:148
	s_waitcnt lgkmcnt(9)
	v_fma_f32 v7, v33, v58, v125
	v_fma_f32 v6, v32, v58, v124
	v_fma_f32 v6, -v33, v0, v6
	v_fma_f32 v0, v32, v0, v7
	v_cvt_pk_bf16_f32 v7, v6, v0
	s_waitcnt lgkmcnt(8)
	v_fma_f32 v58, -v0, v33, v126
	v_fma_f32 v0, v0, v32, v127
	v_fma_f32 v0, v6, v33, v0
	v_fma_f32 v58, v6, v32, v58
	v_cvt_pk_bf16_f32 v6, v58, v0
	ds_write2_b32 v105, v6, v7 offset0:72 offset1:140
	s_waitcnt lgkmcnt(8)
	v_fma_f32 v7, v33, v58, v129
	v_fma_f32 v6, v32, v58, v128
	v_fma_f32 v6, -v33, v0, v6
	v_fma_f32 v7, v32, v0, v7
	v_mul_f32_e32 v0, v33, v7
	v_cvt_pk_bf16_f32 v58, v6, v7
	v_fma_f32 v0, v32, v6, -v0
	v_mul_f32_e32 v6, v33, v6
	v_fmac_f32_e32 v6, v32, v7
	s_waitcnt lgkmcnt(7)
	v_add_f32_e32 v0, v130, v0
	v_add_f32_e32 v6, v131, v6
	v_cvt_pk_bf16_f32 v7, v0, v6
	ds_write2_b32 v106, v7, v58 offset0:64 offset1:132
	s_waitcnt lgkmcnt(0)
	ds_read_b128 v[72:75], v79 offset:11520
	ds_read_b128 v[108:111], v79 offset:11584
	s_waitcnt lgkmcnt(1)
	v_mfma_f32_16x16x32_bf16 v[58:61], v[72:75], v[20:23], v[60:63]
	ds_read_b128 v[72:75], v79 offset:11648
	v_mov_b32_e32 v76, 0
	v_mov_b32_e32 v77, 0
	s_waitcnt lgkmcnt(1)
	v_mfma_f32_16x16x32_bf16 v[58:61], v[108:111], v[28:31], v[58:61]
	ds_read_b128 v[108:111], v79 offset:11712
	s_waitcnt lgkmcnt(1)
	v_mfma_f32_16x16x32_bf16 v[58:61], v[72:75], v[24:27], v[58:61]
	v_mov_b32_e32 v72, 0
	v_mov_b32_e32 v74, 0
	v_mov_b32_e32 v75, 0
	s_waitcnt lgkmcnt(0)
	v_mfma_f32_16x16x32_bf16 v[58:61], v[108:111], v[16:19], v[58:61]
	s_and_saveexec_b64 s[4:5], vcc
	ds_read_b128 v[74:77], v81 offset:768
	s_or_b64 exec, exec, s[4:5]
	s_waitcnt lgkmcnt(0)
	v_mfma_f32_16x16x32_bf16 v[108:111], v[74:77], v[42:45], 0
	v_mul_f32_e32 v7, v33, v6
	v_fma_f32 v7, v32, v0, -v7
	v_mul_f32_e32 v0, v33, v0
	v_mfma_f32_16x16x32_bf16 v[112:115], v[74:77], v[68:71], 0
	s_nop 7
	ds_write2_b32 v80, v108, v112 offset1:16
	ds_write2_b32 v80, v109, v113 offset0:132 offset1:148
	ds_write2_b32 v82, v110, v114 offset0:8 offset1:24
	v_mfma_f32_16x16x32_bf16 v[116:119], v[74:77], v[64:67], 0
	v_fmac_f32_e32 v0, v32, v6
	v_mov_b32_e32 v73, 0
	v_mfma_f32_16x16x32_bf16 v[120:123], v[74:77], v[50:53], 0
	ds_write2_b32 v82, v111, v115 offset0:140 offset1:156
	s_nop 6
	ds_write2_b32 v80, v116, v120 offset0:32 offset1:48
	ds_write2_b32 v80, v117, v121 offset0:164 offset1:180
	v_mfma_f32_16x16x32_bf16 v[124:127], v[74:77], v[54:57], 0
	v_mfma_f32_16x16x32_bf16 v[108:111], v[74:77], v[46:49], 0
	ds_write2_b32 v82, v118, v122 offset0:40 offset1:56
	ds_write2_b32 v82, v119, v123 offset0:172 offset1:188
	s_nop 5
	ds_write2_b32 v80, v124, v108 offset0:64 offset1:80
	ds_write2_b32 v80, v125, v109 offset0:196 offset1:212
	ds_write2_b32 v82, v126, v110 offset0:72 offset1:88
	ds_write2_b32 v82, v127, v111 offset0:204 offset1:220
	v_mfma_f32_16x16x32_bf16 v[112:115], v[74:77], v[38:41], 0
	v_mfma_f32_16x16x32_bf16 v[74:77], v[74:77], v[34:37], 0
	s_nop 7
	ds_write2_b32 v80, v112, v74 offset0:96 offset1:112
	ds_write2_b32 v80, v113, v75 offset0:228 offset1:244
	ds_write2_b32 v82, v114, v76 offset0:104 offset1:120
	ds_write2_b32 v82, v115, v77 offset0:236 offset1:252
	s_waitcnt lgkmcnt(0)
	ds_read2st64_b32 v[62:63], v84 offset0:42 offset1:43
	ds_read2st64_b32 v[74:75], v85 offset0:40 offset1:41
	ds_read2st64_b32 v[76:77], v86 offset0:38 offset1:39
	ds_read2st64_b32 v[108:109], v87 offset0:36 offset1:37
	ds_read2st64_b32 v[110:111], v88 offset0:34 offset1:35
	ds_read2st64_b32 v[112:113], v89 offset0:32 offset1:33
	ds_read2st64_b32 v[114:115], v90 offset0:30 offset1:31
	ds_read2st64_b32 v[116:117], v91 offset0:28 offset1:29
	ds_read2st64_b32 v[118:119], v92 offset0:26 offset1:27
	ds_read2st64_b32 v[120:121], v93 offset0:24 offset1:25
	ds_read2st64_b32 v[122:123], v94 offset0:22 offset1:23
	ds_read2st64_b32 v[124:125], v95 offset0:20 offset1:21
	ds_read2st64_b32 v[126:127], v96 offset0:18 offset1:19
	ds_read2st64_b32 v[128:129], v97 offset0:16 offset1:17
	ds_read2st64_b32 v[130:131], v98 offset0:14 offset1:15
	ds_read2st64_b32 v[132:133], v83 offset0:12 offset1:13
	s_waitcnt lgkmcnt(14)
	v_add_f32_e32 v7, v7, v62
	v_add_f32_e32 v0, v0, v63
	v_cvt_pk_bf16_f32 v6, v7, v0
	v_fma_f32 v62, -v0, v33, v74
	v_fma_f32 v0, v0, v32, v75
	v_fma_f32 v0, v7, v33, v0
	v_fma_f32 v62, v7, v32, v62
	v_cvt_pk_bf16_f32 v7, v62, v0
	ds_write2_b32 v99, v7, v6 offset0:120 offset1:188
	s_waitcnt lgkmcnt(14)
	v_fma_f32 v7, v33, v62, v77
	v_fma_f32 v6, v32, v62, v76
	v_fma_f32 v6, -v33, v0, v6
	v_fma_f32 v0, v32, v0, v7
	v_cvt_pk_bf16_f32 v7, v6, v0
	s_waitcnt lgkmcnt(13)
	v_fma_f32 v62, -v0, v33, v108
	v_fma_f32 v0, v0, v32, v109
	v_fma_f32 v0, v6, v33, v0
	v_fma_f32 v62, v6, v32, v62
	v_cvt_pk_bf16_f32 v6, v62, v0
	ds_write2_b32 v100, v6, v7 offset0:112 offset1:180
	s_waitcnt lgkmcnt(13)
	v_fma_f32 v7, v33, v62, v111
	v_fma_f32 v6, v32, v62, v110
	v_fma_f32 v6, -v33, v0, v6
	v_fma_f32 v0, v32, v0, v7
	v_cvt_pk_bf16_f32 v7, v6, v0
	s_waitcnt lgkmcnt(12)
	v_fma_f32 v62, -v0, v33, v112
	v_fma_f32 v0, v0, v32, v113
	v_fma_f32 v0, v6, v33, v0
	v_fma_f32 v62, v6, v32, v62
	v_cvt_pk_bf16_f32 v6, v62, v0
	ds_write2_b32 v101, v6, v7 offset0:104 offset1:172
	s_waitcnt lgkmcnt(12)
	v_fma_f32 v7, v33, v62, v115
	v_fma_f32 v6, v32, v62, v114
	v_fma_f32 v6, -v33, v0, v6
	v_fma_f32 v0, v32, v0, v7
	v_cvt_pk_bf16_f32 v7, v6, v0
	s_waitcnt lgkmcnt(11)
	v_fma_f32 v62, -v0, v33, v116
	v_fma_f32 v0, v0, v32, v117
	v_fma_f32 v0, v6, v33, v0
	v_fma_f32 v62, v6, v32, v62
	v_cvt_pk_bf16_f32 v6, v62, v0
	ds_write2_b32 v102, v6, v7 offset0:96 offset1:164
	s_waitcnt lgkmcnt(11)
	v_fma_f32 v7, v33, v62, v119
	v_fma_f32 v6, v32, v62, v118
	v_fma_f32 v6, -v33, v0, v6
	v_fma_f32 v0, v32, v0, v7
	v_cvt_pk_bf16_f32 v7, v6, v0
	s_waitcnt lgkmcnt(10)
	v_fma_f32 v62, -v0, v33, v120
	v_fma_f32 v0, v0, v32, v121
	v_fma_f32 v0, v6, v33, v0
	v_fma_f32 v62, v6, v32, v62
	v_cvt_pk_bf16_f32 v6, v62, v0
	ds_write2_b32 v103, v6, v7 offset0:88 offset1:156
	s_waitcnt lgkmcnt(10)
	v_fma_f32 v7, v33, v62, v123
	v_fma_f32 v6, v32, v62, v122
	v_fma_f32 v6, -v33, v0, v6
	v_fma_f32 v0, v32, v0, v7
	v_cvt_pk_bf16_f32 v7, v6, v0
	s_waitcnt lgkmcnt(9)
	v_fma_f32 v62, -v0, v33, v124
	v_fma_f32 v0, v0, v32, v125
	v_fma_f32 v0, v6, v33, v0
	v_fma_f32 v62, v6, v32, v62
	v_cvt_pk_bf16_f32 v6, v62, v0
	ds_write2_b32 v104, v6, v7 offset0:80 offset1:148
	s_waitcnt lgkmcnt(9)
	v_fma_f32 v7, v33, v62, v127
	v_fma_f32 v6, v32, v62, v126
	v_fma_f32 v6, -v33, v0, v6
	v_fma_f32 v0, v32, v0, v7
	v_cvt_pk_bf16_f32 v7, v6, v0
	s_waitcnt lgkmcnt(8)
	v_fma_f32 v62, -v0, v33, v128
	v_fma_f32 v0, v0, v32, v129
	v_fma_f32 v0, v6, v33, v0
	v_fma_f32 v62, v6, v32, v62
	v_cvt_pk_bf16_f32 v6, v62, v0
	ds_write2_b32 v105, v6, v7 offset0:72 offset1:140
	s_waitcnt lgkmcnt(8)
	v_fma_f32 v7, v33, v62, v131
	v_fma_f32 v6, v32, v62, v130
	v_fma_f32 v6, -v33, v0, v6
	v_fma_f32 v7, v32, v0, v7
	v_cvt_pk_bf16_f32 v63, v6, v7
	s_waitcnt lgkmcnt(7)
	v_fma_f32 v0, -v33, v7, v132
	v_fma_f32 v62, v33, v6, v133
	v_fma_f32 v62, v32, v7, v62
	v_fma_f32 v0, v32, v6, v0
	v_cvt_pk_bf16_f32 v6, v0, v62
	ds_write2_b32 v106, v6, v63 offset0:64 offset1:132
	s_waitcnt lgkmcnt(0)
	ds_read_b128 v[74:77], v79 offset:11520
	ds_read_b128 v[108:111], v79 offset:11584
	s_waitcnt lgkmcnt(1)
	v_mfma_f32_16x16x32_bf16 v[6:9], v[74:77], v[20:23], v[8:11]
	ds_read_b128 v[74:77], v79 offset:11648
	s_waitcnt lgkmcnt(1)
	v_mfma_f32_16x16x32_bf16 v[6:9], v[108:111], v[28:31], v[6:9]
	ds_read_b128 v[108:111], v79 offset:11712
	s_waitcnt lgkmcnt(1)
	v_mfma_f32_16x16x32_bf16 v[6:9], v[74:77], v[24:27], v[6:9]
	v_mov_b32_e32 v74, 0
	v_mov_b32_e32 v75, 0
	s_waitcnt lgkmcnt(0)
	v_mfma_f32_16x16x32_bf16 v[6:9], v[108:111], v[16:19], v[6:9]
	s_and_saveexec_b64 s[4:5], vcc
	s_cbranch_execz .LBB0_275
	ds_read_b128 v[72:75], v81
	s_branch .LBB0_275
